# GQA fast loop: kh loop unrolled, K/V fragment addresses hoisted per tile, LDS waits merged (8 instead of 19 per body)
# speedup vs baseline: 1.0099x; 1.0099x over previous
; #define MFMA32(a, b, c) __builtin_amdgcn_mfma_f32_32x32x16_bf16((a), (b), (c), 0, 0, 0)
; DI float fadd1(float a, float b) { float r; asm("v_add_f32 %0, %1, %2" : "=v"(r) : "v"(a), "v"(b)); return r; }
; template <int NKS>
; DI void attn_tile(const Params& p, int layer, int seq, int slot, int qt, char* smem, bool wr = true) {
;     ...
; #pragma unroll 1
;       for (int kh = 0; kh < 2; ++kh) {
;       const u16* sK = (const u16*)(smem + (kt & 1) * 32768 + kh * 8192);
;       const u16* sV = (const u16*)(smem + (kt & 1) * 32768 + 16384 + kh * 8192);
;       auto kb_body = [&](int kb) {
;         bf16x8 kf[NKS];
; #pragma unroll
;         for (int ks = 0; ks < NKS; ++ks) kf[ks] = *(const bf16x8*)(sK + swz(32 * kb + r, 2 * (ks0 + ks) + h));
;         bf16x8 pk[2][2];
; #pragma unroll
;         for (int qb = 0; qb < 2; ++qb) {
;           f32x16 st;
; #pragma unroll
;           for (int i = 0; i < 16; ++i) st[i] = SUB ? ncb[qb] : 0.f;
; #pragma unroll
;           for (int ks = 0; ks < NKS; ++ks) st = MFMA32(kf[ks], qf[qb][ks], st);
;           if constexpr (SUB) {
;             float ls = 0.f;
; #pragma unroll
;             for (int i = 0; i < 16; ++i) { float e = __builtin_amdgcn_exp2f(st[i]); st[i] = e; ls = fadd1(ls, e); }
;             lsum[qb] += ls;
;             pk[qb][0] = pack8(st, 0); pk[qb][1] = pack8(st, 1);
;           } else {
; #pragma unroll
;             for (int i = 0; i < 16; ++i) st[i] = __builtin_amdgcn_exp2f(st[i]);
;             pk[qb][0] = pack8(st, 0); pk[qb][1] = pack8(st, 1);
;             ls4[qb] = __builtin_amdgcn_mfma_f32_16x16x32_bf16(selA, pk[qb][0], ls4[qb], 0, 0, 0);
;             ls4[qb] = __builtin_amdgcn_mfma_f32_16x16x32_bf16(selA, pk[qb][1], ls4[qb], 0, 0, 0);
;           }
;         }
; #pragma unroll
;         for (int eb = 0; eb < 2; ++eb)
; #pragma unroll
;           for (int s2 = 0; s2 < 2; ++s2) {
;             bf16x8 vf = *(const bf16x8*)(sV + swz(32 * eb + r, 4 * kb + 2 * s2 + h));
; #pragma unroll
;             for (int qb = 0; qb < 2; ++qb) O[qb][eb] = MFMA32(vf, pk[qb][s2], O[qb][eb]);
;           }
;       };
.LBB0_640:
	v_lshl_add_u32 v128, v187, 1, s14
	v_lshl_add_u32 v130, v188, 1, s14
	v_lshl_add_u32 v131, v189, 1, s14
	v_lshl_add_u32 v191, v190, 1, s14
	ds_read_b128 v[192:195], v128
	ds_read_b128 v[196:199], v130
	ds_read_b128 v[200:203], v131
	ds_read_b128 v[204:207], v191
	ds_read_b128 v[208:211], v128 offset:4096
	ds_read_b128 v[212:215], v130 offset:4096
	ds_read_b128 v[216:219], v131 offset:4096
	ds_read_b128 v[220:223], v191 offset:4096
	ds_read_b128 v[224:227], v128 offset:16384
	ds_read_b128 v[228:231], v128 offset:20480
	s_waitcnt lgkmcnt(8)
	v_mfma_f32_32x32x16_bf16 v[112:127], v[192:195], v[132:135], 0
	v_mfma_f32_32x32x16_bf16 v[112:127], v[196:199], v[136:139], v[112:127]
	s_waitcnt lgkmcnt(6)
	v_mfma_f32_32x32x16_bf16 v[112:127], v[200:203], v[140:143], v[112:127]
	v_mfma_f32_32x32x16_bf16 v[112:127], v[204:207], v[144:147], v[112:127]
	v_mfma_f32_32x32x16_bf16 v[96:111], v[192:195], v[148:151], 0
	v_mfma_f32_32x32x16_bf16 v[96:111], v[196:199], v[152:155], v[96:111]
	v_mfma_f32_32x32x16_bf16 v[96:111], v[200:203], v[156:159], v[96:111]
	v_mfma_f32_32x32x16_bf16 v[96:111], v[204:207], v[160:163], v[96:111]
	ds_read_b128 v[192:195], v130 offset:16384
	ds_read_b128 v[196:199], v130 offset:20480
	ds_read_b128 v[200:203], v131 offset:16384
	ds_read_b128 v[204:207], v131 offset:20480
	s_waitcnt lgkmcnt(9)
	v_mfma_f32_32x32x16_bf16 v[64:79], v[208:211], v[132:135], 0
	s_nop 1
	v_exp_f32_e32 v112, v112
	v_exp_f32_e32 v113, v113
	v_exp_f32_e32 v114, v114
	v_exp_f32_e32 v115, v115
	v_cvt_pk_bf16_f32 v112, v112, v113
	v_cvt_pk_bf16_f32 v113, v114, v115
	s_waitcnt lgkmcnt(6)
	v_mfma_f32_32x32x16_bf16 v[64:79], v[212:215], v[136:139], v[64:79]
	v_exp_f32_e32 v116, v116
	v_exp_f32_e32 v117, v117
	v_exp_f32_e32 v118, v118
	v_exp_f32_e32 v119, v119
	v_cvt_pk_bf16_f32 v114, v116, v117
	v_cvt_pk_bf16_f32 v115, v118, v119
	v_mfma_f32_32x32x16_bf16 v[64:79], v[216:219], v[140:143], v[64:79]
	v_exp_f32_e32 v120, v120
	v_exp_f32_e32 v121, v121
	v_exp_f32_e32 v122, v122
	v_exp_f32_e32 v123, v123
	v_cvt_pk_bf16_f32 v116, v120, v121
	v_cvt_pk_bf16_f32 v117, v122, v123
	v_mfma_f32_32x32x16_bf16 v[64:79], v[220:223], v[144:147], v[64:79]
	s_waitcnt lgkmcnt(4)
	v_mfma_f32_32x32x16_bf16 v[48:63], v[224:227], v[112:115], v[48:63]
	v_exp_f32_e32 v124, v124
	v_exp_f32_e32 v125, v125
	v_exp_f32_e32 v126, v126
	v_exp_f32_e32 v127, v127
	v_cvt_pk_bf16_f32 v118, v124, v125
	v_cvt_pk_bf16_f32 v119, v126, v127
	v_mfma_f32_32x32x16_bf16 v[80:95], v[208:211], v[148:151], 0
	v_mfma_f32_32x32x16_bf16 v[32:47], v[228:231], v[112:115], v[32:47]
	v_exp_f32_e32 v96, v96
	v_exp_f32_e32 v97, v97
	v_exp_f32_e32 v98, v98
	v_exp_f32_e32 v99, v99
	v_cvt_pk_bf16_f32 v96, v96, v97
	v_cvt_pk_bf16_f32 v97, v98, v99
	v_mfma_f32_16x16x32_bf16 v[164:167], v[172:175], v[112:115], v[164:167]
	v_mfma_f32_32x32x16_bf16 v[80:95], v[212:215], v[152:155], v[80:95]
	v_exp_f32_e32 v100, v100
	v_exp_f32_e32 v101, v101
	v_exp_f32_e32 v102, v102
	v_exp_f32_e32 v103, v103
	v_cvt_pk_bf16_f32 v98, v100, v101
	v_cvt_pk_bf16_f32 v99, v102, v103
	v_mfma_f32_32x32x16_bf16 v[80:95], v[216:219], v[156:159], v[80:95]
	s_waitcnt lgkmcnt(2)
	v_mfma_f32_32x32x16_bf16 v[48:63], v[192:195], v[116:119], v[48:63]
	v_exp_f32_e32 v104, v104
	v_exp_f32_e32 v105, v105
	v_exp_f32_e32 v106, v106
	v_exp_f32_e32 v107, v107
	v_cvt_pk_bf16_f32 v100, v104, v105
	v_cvt_pk_bf16_f32 v101, v106, v107
	v_mfma_f32_32x32x16_bf16 v[32:47], v[196:199], v[116:119], v[32:47]
	v_mfma_f32_16x16x32_bf16 v[164:167], v[172:175], v[116:119], v[164:167]
	v_exp_f32_e32 v108, v108
	v_exp_f32_e32 v109, v109
	v_exp_f32_e32 v110, v110
	v_exp_f32_e32 v111, v111
	v_cvt_pk_bf16_f32 v102, v108, v109
	v_cvt_pk_bf16_f32 v103, v110, v111
	v_mfma_f32_32x32x16_bf16 v[80:95], v[220:223], v[160:163], v[80:95]
	ds_read_b128 v[208:211], v191 offset:16384
	ds_read_b128 v[212:215], v191 offset:20480
	v_mfma_f32_32x32x16_bf16 v[16:31], v[224:227], v[96:99], v[16:31]
	v_exp_f32_e32 v64, v64
	v_exp_f32_e32 v65, v65
	v_exp_f32_e32 v66, v66
	v_exp_f32_e32 v67, v67
	v_cvt_pk_bf16_f32 v64, v64, v65
	v_cvt_pk_bf16_f32 v65, v66, v67
	v_mfma_f32_32x32x16_bf16 v[0:15], v[228:231], v[96:99], v[0:15]
	v_mfma_f32_16x16x32_bf16 v[168:171], v[172:175], v[96:99], v[168:171]
	v_exp_f32_e32 v68, v68
	v_exp_f32_e32 v69, v69
	v_exp_f32_e32 v70, v70
	v_exp_f32_e32 v71, v71
	v_cvt_pk_bf16_f32 v66, v68, v69
	v_cvt_pk_bf16_f32 v67, v70, v71
	v_mfma_f32_32x32x16_bf16 v[16:31], v[192:195], v[100:103], v[16:31]
	v_mfma_f32_32x32x16_bf16 v[0:15], v[196:199], v[100:103], v[0:15]
	v_exp_f32_e32 v72, v72
	v_exp_f32_e32 v73, v73
	v_exp_f32_e32 v74, v74
	v_exp_f32_e32 v75, v75
	v_cvt_pk_bf16_f32 v68, v72, v73
	v_cvt_pk_bf16_f32 v69, v74, v75
	v_mfma_f32_16x16x32_bf16 v[168:171], v[172:175], v[100:103], v[168:171]
	s_waitcnt lgkmcnt(2)
	v_mfma_f32_32x32x16_bf16 v[48:63], v[200:203], v[64:67], v[48:63]
	v_exp_f32_e32 v76, v76
	v_exp_f32_e32 v77, v77
	v_exp_f32_e32 v78, v78
	v_exp_f32_e32 v79, v79
	v_cvt_pk_bf16_f32 v70, v76, v77
	v_cvt_pk_bf16_f32 v71, v78, v79
	v_mfma_f32_32x32x16_bf16 v[32:47], v[204:207], v[64:67], v[32:47]
	v_mfma_f32_16x16x32_bf16 v[164:167], v[172:175], v[64:67], v[164:167]
	v_exp_f32_e32 v80, v80
	v_exp_f32_e32 v81, v81
	v_exp_f32_e32 v82, v82
	v_exp_f32_e32 v83, v83
	v_cvt_pk_bf16_f32 v80, v80, v81
	v_cvt_pk_bf16_f32 v81, v82, v83
	s_waitcnt lgkmcnt(0)
; #define MFMA32(a, b, c) __builtin_amdgcn_mfma_f32_32x32x16_bf16((a), (b), (c), 0, 0, 0)
; DI float fadd1(float a, float b) { float r; asm("v_add_f32 %0, %1, %2" : "=v"(r) : "v"(a), "v"(b)); return r; }
; template <int NKS>
; DI void attn_tile(const Params& p, int layer, int seq, int slot, int qt, char* smem, bool wr = true) {
;     ...
; #pragma unroll 1
;       for (int kh = 0; kh < 2; ++kh) {
;       const u16* sK = (const u16*)(smem + (kt & 1) * 32768 + kh * 8192);
;       const u16* sV = (const u16*)(smem + (kt & 1) * 32768 + 16384 + kh * 8192);
;       auto kb_body = [&](int kb) {
;         bf16x8 kf[NKS];
; #pragma unroll
;         for (int ks = 0; ks < NKS; ++ks) kf[ks] = *(const bf16x8*)(sK + swz(32 * kb + r, 2 * (ks0 + ks) + h));
;         bf16x8 pk[2][2];
; #pragma unroll
;         for (int qb = 0; qb < 2; ++qb) {
;           f32x16 st;
; #pragma unroll
;           for (int i = 0; i < 16; ++i) st[i] = SUB ? ncb[qb] : 0.f;
; #pragma unroll
;           for (int ks = 0; ks < NKS; ++ks) st = MFMA32(kf[ks], qf[qb][ks], st);
;           if constexpr (SUB) {
;             float ls = 0.f;
; #pragma unroll
;             for (int i = 0; i < 16; ++i) { float e = __builtin_amdgcn_exp2f(st[i]); st[i] = e; ls = fadd1(ls, e); }
;             lsum[qb] += ls;
;             pk[qb][0] = pack8(st, 0); pk[qb][1] = pack8(st, 1);
;           } else {
; #pragma unroll
;             for (int i = 0; i < 16; ++i) st[i] = __builtin_amdgcn_exp2f(st[i]);
;             pk[qb][0] = pack8(st, 0); pk[qb][1] = pack8(st, 1);
;             ls4[qb] = __builtin_amdgcn_mfma_f32_16x16x32_bf16(selA, pk[qb][0], ls4[qb], 0, 0, 0);
;             ls4[qb] = __builtin_amdgcn_mfma_f32_16x16x32_bf16(selA, pk[qb][1], ls4[qb], 0, 0, 0);
;           }
;         }
; #pragma unroll
;         for (int eb = 0; eb < 2; ++eb)
; #pragma unroll
;           for (int s2 = 0; s2 < 2; ++s2) {
;             bf16x8 vf = *(const bf16x8*)(sV + swz(32 * eb + r, 4 * kb + 2 * s2 + h));
; #pragma unroll
;             for (int qb = 0; qb < 2; ++qb) O[qb][eb] = MFMA32(vf, pk[qb][s2], O[qb][eb]);
;           }
;       };
;       if constexpr (SUB) {
; #pragma unroll 1
;         for (int kb = 0; kb < 2; ++kb) kb_body(kb);
;       } else {
;         kb_body(0); kb_body(1);
	v_mfma_f32_32x32x16_bf16 v[48:63], v[208:211], v[68:71], v[48:63]
	v_exp_f32_e32 v84, v84
	v_exp_f32_e32 v85, v85
	v_exp_f32_e32 v86, v86
	v_exp_f32_e32 v87, v87
	v_cvt_pk_bf16_f32 v82, v84, v85
	v_cvt_pk_bf16_f32 v83, v86, v87
	v_mfma_f32_32x32x16_bf16 v[32:47], v[212:215], v[68:71], v[32:47]
	v_mfma_f32_16x16x32_bf16 v[164:167], v[172:175], v[68:71], v[164:167]
	v_exp_f32_e32 v88, v88
	v_exp_f32_e32 v89, v89
	v_exp_f32_e32 v90, v90
	v_exp_f32_e32 v91, v91
	v_cvt_pk_bf16_f32 v84, v88, v89
	v_cvt_pk_bf16_f32 v85, v90, v91
	v_mfma_f32_32x32x16_bf16 v[16:31], v[200:203], v[80:83], v[16:31]
	v_exp_f32_e32 v92, v92
	v_exp_f32_e32 v93, v93
	v_exp_f32_e32 v94, v94
	v_exp_f32_e32 v95, v95
	v_cvt_pk_bf16_f32 v86, v92, v93
	v_cvt_pk_bf16_f32 v87, v94, v95
	v_mfma_f32_32x32x16_bf16 v[0:15], v[204:207], v[80:83], v[0:15]
	v_mfma_f32_16x16x32_bf16 v[168:171], v[172:175], v[80:83], v[168:171]
	v_mfma_f32_32x32x16_bf16 v[16:31], v[208:211], v[84:87], v[16:31]
	v_mfma_f32_32x32x16_bf16 v[0:15], v[212:215], v[84:87], v[0:15]
	v_mfma_f32_16x16x32_bf16 v[168:171], v[172:175], v[84:87], v[168:171]
	ds_read_b128 v[192:195], v128 offset:8192
	ds_read_b128 v[196:199], v130 offset:8192
	ds_read_b128 v[200:203], v131 offset:8192
	ds_read_b128 v[204:207], v191 offset:8192
	ds_read_b128 v[208:211], v128 offset:12288
	ds_read_b128 v[212:215], v130 offset:12288
	ds_read_b128 v[216:219], v131 offset:12288
	ds_read_b128 v[220:223], v191 offset:12288
	ds_read_b128 v[224:227], v128 offset:24576
	ds_read_b128 v[228:231], v128 offset:28672
	s_waitcnt lgkmcnt(8)
	v_mfma_f32_32x32x16_bf16 v[112:127], v[192:195], v[132:135], 0
	v_mfma_f32_32x32x16_bf16 v[112:127], v[196:199], v[136:139], v[112:127]
	s_waitcnt lgkmcnt(6)
	v_mfma_f32_32x32x16_bf16 v[112:127], v[200:203], v[140:143], v[112:127]
	v_mfma_f32_32x32x16_bf16 v[112:127], v[204:207], v[144:147], v[112:127]
	v_mfma_f32_32x32x16_bf16 v[96:111], v[192:195], v[148:151], 0
	v_mfma_f32_32x32x16_bf16 v[96:111], v[196:199], v[152:155], v[96:111]
	v_mfma_f32_32x32x16_bf16 v[96:111], v[200:203], v[156:159], v[96:111]
	v_mfma_f32_32x32x16_bf16 v[96:111], v[204:207], v[160:163], v[96:111]
	ds_read_b128 v[192:195], v130 offset:24576
	ds_read_b128 v[196:199], v130 offset:28672
	ds_read_b128 v[200:203], v131 offset:24576
	ds_read_b128 v[204:207], v131 offset:28672
	s_waitcnt lgkmcnt(9)
	v_mfma_f32_32x32x16_bf16 v[64:79], v[208:211], v[132:135], 0
	s_nop 1
	v_exp_f32_e32 v112, v112
	v_exp_f32_e32 v113, v113
	v_exp_f32_e32 v114, v114
	v_exp_f32_e32 v115, v115
	v_cvt_pk_bf16_f32 v112, v112, v113
	v_cvt_pk_bf16_f32 v113, v114, v115
	s_waitcnt lgkmcnt(6)
	v_mfma_f32_32x32x16_bf16 v[64:79], v[212:215], v[136:139], v[64:79]
	v_exp_f32_e32 v116, v116
	v_exp_f32_e32 v117, v117
	v_exp_f32_e32 v118, v118
	v_exp_f32_e32 v119, v119
	v_cvt_pk_bf16_f32 v114, v116, v117
	v_cvt_pk_bf16_f32 v115, v118, v119
	v_mfma_f32_32x32x16_bf16 v[64:79], v[216:219], v[140:143], v[64:79]
	v_exp_f32_e32 v120, v120
	v_exp_f32_e32 v121, v121
	v_exp_f32_e32 v122, v122
	v_exp_f32_e32 v123, v123
	v_cvt_pk_bf16_f32 v116, v120, v121
	v_cvt_pk_bf16_f32 v117, v122, v123
	v_mfma_f32_32x32x16_bf16 v[64:79], v[220:223], v[144:147], v[64:79]
	s_waitcnt lgkmcnt(4)
	v_mfma_f32_32x32x16_bf16 v[48:63], v[224:227], v[112:115], v[48:63]
	v_exp_f32_e32 v124, v124
	v_exp_f32_e32 v125, v125
	v_exp_f32_e32 v126, v126
	v_exp_f32_e32 v127, v127
	v_cvt_pk_bf16_f32 v118, v124, v125
	v_cvt_pk_bf16_f32 v119, v126, v127
	v_mfma_f32_32x32x16_bf16 v[80:95], v[208:211], v[148:151], 0
	v_mfma_f32_32x32x16_bf16 v[32:47], v[228:231], v[112:115], v[32:47]
	v_exp_f32_e32 v96, v96
	v_exp_f32_e32 v97, v97
	v_exp_f32_e32 v98, v98
	v_exp_f32_e32 v99, v99
	v_cvt_pk_bf16_f32 v96, v96, v97
	v_cvt_pk_bf16_f32 v97, v98, v99
	v_mfma_f32_16x16x32_bf16 v[164:167], v[172:175], v[112:115], v[164:167]
	v_mfma_f32_32x32x16_bf16 v[80:95], v[212:215], v[152:155], v[80:95]
	v_exp_f32_e32 v100, v100
	v_exp_f32_e32 v101, v101
	v_exp_f32_e32 v102, v102
	v_exp_f32_e32 v103, v103
	v_cvt_pk_bf16_f32 v98, v100, v101
	v_cvt_pk_bf16_f32 v99, v102, v103
	v_mfma_f32_32x32x16_bf16 v[80:95], v[216:219], v[156:159], v[80:95]
	s_waitcnt lgkmcnt(2)
; #define MFMA32(a, b, c) __builtin_amdgcn_mfma_f32_32x32x16_bf16((a), (b), (c), 0, 0, 0)
; DI float fadd1(float a, float b) { float r; asm("v_add_f32 %0, %1, %2" : "=v"(r) : "v"(a), "v"(b)); return r; }
; template <int NKS>
; DI void attn_tile(const Params& p, int layer, int seq, int slot, int qt, char* smem, bool wr = true) {
;     ...
;       auto kb_body = [&](int kb) {
;         bf16x8 kf[NKS];
; #pragma unroll
;         for (int ks = 0; ks < NKS; ++ks) kf[ks] = *(const bf16x8*)(sK + swz(32 * kb + r, 2 * (ks0 + ks) + h));
;         bf16x8 pk[2][2];
; #pragma unroll
;         for (int qb = 0; qb < 2; ++qb) {
;           f32x16 st;
; #pragma unroll
;           for (int i = 0; i < 16; ++i) st[i] = SUB ? ncb[qb] : 0.f;
; #pragma unroll
;           for (int ks = 0; ks < NKS; ++ks) st = MFMA32(kf[ks], qf[qb][ks], st);
;           if constexpr (SUB) {
;             float ls = 0.f;
; #pragma unroll
;             for (int i = 0; i < 16; ++i) { float e = __builtin_amdgcn_exp2f(st[i]); st[i] = e; ls = fadd1(ls, e); }
;             lsum[qb] += ls;
;             pk[qb][0] = pack8(st, 0); pk[qb][1] = pack8(st, 1);
;           } else {
; #pragma unroll
;             for (int i = 0; i < 16; ++i) st[i] = __builtin_amdgcn_exp2f(st[i]);
;             pk[qb][0] = pack8(st, 0); pk[qb][1] = pack8(st, 1);
;             ls4[qb] = __builtin_amdgcn_mfma_f32_16x16x32_bf16(selA, pk[qb][0], ls4[qb], 0, 0, 0);
;             ls4[qb] = __builtin_amdgcn_mfma_f32_16x16x32_bf16(selA, pk[qb][1], ls4[qb], 0, 0, 0);
;           }
;         }
; #pragma unroll
;         for (int eb = 0; eb < 2; ++eb)
; #pragma unroll
;           for (int s2 = 0; s2 < 2; ++s2) {
;             bf16x8 vf = *(const bf16x8*)(sV + swz(32 * eb + r, 4 * kb + 2 * s2 + h));
; #pragma unroll
;             for (int qb = 0; qb < 2; ++qb) O[qb][eb] = MFMA32(vf, pk[qb][s2], O[qb][eb]);
;           }
;       };
;       if constexpr (SUB) {
; #pragma unroll 1
;         for (int kb = 0; kb < 2; ++kb) kb_body(kb);
;       } else {
;         kb_body(0); kb_body(1);
;       }
;       }
;     }
	v_mfma_f32_32x32x16_bf16 v[48:63], v[192:195], v[116:119], v[48:63]
	v_exp_f32_e32 v104, v104
	v_exp_f32_e32 v105, v105
	v_exp_f32_e32 v106, v106
	v_exp_f32_e32 v107, v107
	v_cvt_pk_bf16_f32 v100, v104, v105
	v_cvt_pk_bf16_f32 v101, v106, v107
	v_mfma_f32_32x32x16_bf16 v[32:47], v[196:199], v[116:119], v[32:47]
	v_mfma_f32_16x16x32_bf16 v[164:167], v[172:175], v[116:119], v[164:167]
	v_exp_f32_e32 v108, v108
	v_exp_f32_e32 v109, v109
	v_exp_f32_e32 v110, v110
	v_exp_f32_e32 v111, v111
	v_cvt_pk_bf16_f32 v102, v108, v109
	v_cvt_pk_bf16_f32 v103, v110, v111
	v_mfma_f32_32x32x16_bf16 v[80:95], v[220:223], v[160:163], v[80:95]
	ds_read_b128 v[208:211], v191 offset:24576
	ds_read_b128 v[212:215], v191 offset:28672
	v_mfma_f32_32x32x16_bf16 v[16:31], v[224:227], v[96:99], v[16:31]
	v_exp_f32_e32 v64, v64
	v_exp_f32_e32 v65, v65
	v_exp_f32_e32 v66, v66
	v_exp_f32_e32 v67, v67
	v_cvt_pk_bf16_f32 v64, v64, v65
	v_cvt_pk_bf16_f32 v65, v66, v67
	v_mfma_f32_32x32x16_bf16 v[0:15], v[228:231], v[96:99], v[0:15]
	v_mfma_f32_16x16x32_bf16 v[168:171], v[172:175], v[96:99], v[168:171]
	v_exp_f32_e32 v68, v68
	v_exp_f32_e32 v69, v69
	v_exp_f32_e32 v70, v70
	v_exp_f32_e32 v71, v71
	v_cvt_pk_bf16_f32 v66, v68, v69
	v_cvt_pk_bf16_f32 v67, v70, v71
	v_mfma_f32_32x32x16_bf16 v[16:31], v[192:195], v[100:103], v[16:31]
	v_mfma_f32_32x32x16_bf16 v[0:15], v[196:199], v[100:103], v[0:15]
	v_exp_f32_e32 v72, v72
	v_exp_f32_e32 v73, v73
	v_exp_f32_e32 v74, v74
	v_exp_f32_e32 v75, v75
	v_cvt_pk_bf16_f32 v68, v72, v73
	v_cvt_pk_bf16_f32 v69, v74, v75
	v_mfma_f32_16x16x32_bf16 v[168:171], v[172:175], v[100:103], v[168:171]
	s_waitcnt lgkmcnt(2)
	v_mfma_f32_32x32x16_bf16 v[48:63], v[200:203], v[64:67], v[48:63]
	v_exp_f32_e32 v76, v76
	v_exp_f32_e32 v77, v77
	v_exp_f32_e32 v78, v78
	v_exp_f32_e32 v79, v79
	v_cvt_pk_bf16_f32 v70, v76, v77
	v_cvt_pk_bf16_f32 v71, v78, v79
	v_mfma_f32_32x32x16_bf16 v[32:47], v[204:207], v[64:67], v[32:47]
	v_mfma_f32_16x16x32_bf16 v[164:167], v[172:175], v[64:67], v[164:167]
	v_exp_f32_e32 v80, v80
	v_exp_f32_e32 v81, v81
	v_exp_f32_e32 v82, v82
	v_exp_f32_e32 v83, v83
	v_cvt_pk_bf16_f32 v80, v80, v81
	v_cvt_pk_bf16_f32 v81, v82, v83
	s_waitcnt lgkmcnt(0)
	v_mfma_f32_32x32x16_bf16 v[48:63], v[208:211], v[68:71], v[48:63]
	v_exp_f32_e32 v84, v84
	v_exp_f32_e32 v85, v85
	v_exp_f32_e32 v86, v86
	v_exp_f32_e32 v87, v87
	v_cvt_pk_bf16_f32 v82, v84, v85
	v_cvt_pk_bf16_f32 v83, v86, v87
	v_mfma_f32_32x32x16_bf16 v[32:47], v[212:215], v[68:71], v[32:47]
	v_mfma_f32_16x16x32_bf16 v[164:167], v[172:175], v[68:71], v[164:167]
	v_exp_f32_e32 v88, v88
	v_exp_f32_e32 v89, v89
	v_exp_f32_e32 v90, v90
	v_exp_f32_e32 v91, v91
	v_cvt_pk_bf16_f32 v84, v88, v89
	v_cvt_pk_bf16_f32 v85, v90, v91
	v_mfma_f32_32x32x16_bf16 v[16:31], v[200:203], v[80:83], v[16:31]
	v_exp_f32_e32 v92, v92
	v_exp_f32_e32 v93, v93
	v_exp_f32_e32 v94, v94
	v_exp_f32_e32 v95, v95
	v_cvt_pk_bf16_f32 v86, v92, v93
	v_cvt_pk_bf16_f32 v87, v94, v95
	v_mfma_f32_32x32x16_bf16 v[0:15], v[204:207], v[80:83], v[0:15]
	v_mfma_f32_16x16x32_bf16 v[168:171], v[172:175], v[80:83], v[168:171]
	v_mfma_f32_32x32x16_bf16 v[16:31], v[208:211], v[84:87], v[16:31]
	v_mfma_f32_32x32x16_bf16 v[0:15], v[212:215], v[84:87], v[0:15]
	v_mfma_f32_16x16x32_bf16 v[168:171], v[172:175], v[84:87], v[168:171]
	s_cmp_eq_u32 s28, s25
	s_cbranch_scc1 .LBB0_643
	s_mov_b32 s29, s28
	s_branch .LBB0_637
